# accumulator zeroing between GEMM tiles with 64 v_mov_b64 instead of 128 v_mov_b32
# speedup vs baseline: 1.0017x; 1.0017x over previous
.LBB0_66:
	s_ashr_i32 s25, s24, 31
	s_lshl_b64 s[26:27], s[24:25], 20
	s_add_u32 s26, s38, s26
	s_addc_u32 s27, s39, s27
	s_and_b64 s[30:31], s[4:5], exec
	s_cselect_b32 s25, s27, s7
	s_cselect_b32 s29, s26, s6
	s_ashr_i32 s23, s22, 31
	s_lshl_b64 s[30:31], s[22:23], 20
	s_add_u32 s30, s40, s30
	s_addc_u32 s31, s41, s31
	s_and_b64 s[36:37], s[4:5], exec
	s_cselect_b32 s23, s31, s35
	s_cselect_b32 s49, s30, s34
	s_add_u32 s6, s6, 0x80080
	s_addc_u32 s7, s7, 0
	s_add_u32 s50, s34, 0x100
	s_addc_u32 s51, s35, 0
	s_mov_b32 s52, -2
	v_mov_b64_e32 v[2:3], 0
	v_mov_b64_e32 v[4:5], 0
	v_mov_b64_e32 v[6:7], 0
	v_mov_b64_e32 v[8:9], 0
	v_mov_b64_e32 v[10:11], 0
	v_mov_b64_e32 v[12:13], 0
	v_mov_b64_e32 v[14:15], 0
	v_mov_b64_e32 v[16:17], 0
	v_mov_b64_e32 v[18:19], 0
	v_mov_b64_e32 v[20:21], 0
	v_mov_b64_e32 v[22:23], 0
	v_mov_b64_e32 v[24:25], 0
	v_mov_b64_e32 v[26:27], 0
	v_mov_b64_e32 v[28:29], 0
	v_mov_b64_e32 v[30:31], 0
	v_mov_b64_e32 v[32:33], 0
	v_mov_b64_e32 v[34:35], 0
	v_mov_b64_e32 v[36:37], 0
	v_mov_b64_e32 v[38:39], 0
	v_mov_b64_e32 v[40:41], 0
	v_mov_b64_e32 v[42:43], 0
	v_mov_b64_e32 v[44:45], 0
	v_mov_b64_e32 v[46:47], 0
	v_mov_b64_e32 v[48:49], 0
	v_mov_b64_e32 v[50:51], 0
	v_mov_b64_e32 v[52:53], 0
	v_mov_b64_e32 v[54:55], 0
	v_mov_b64_e32 v[56:57], 0
	v_mov_b64_e32 v[58:59], 0
	v_mov_b64_e32 v[60:61], 0
	v_mov_b64_e32 v[62:63], 0
	v_mov_b64_e32 v[64:65], 0
	v_mov_b64_e32 v[66:67], 0
	v_mov_b64_e32 v[68:69], 0
	v_mov_b64_e32 v[70:71], 0
	v_mov_b64_e32 v[72:73], 0
	v_mov_b64_e32 v[74:75], 0
	v_mov_b64_e32 v[76:77], 0
	v_mov_b64_e32 v[78:79], 0
	v_mov_b64_e32 v[80:81], 0
	v_mov_b64_e32 v[82:83], 0
	v_mov_b64_e32 v[84:85], 0
	v_mov_b64_e32 v[86:87], 0
	v_mov_b64_e32 v[88:89], 0
	v_mov_b64_e32 v[90:91], 0
	v_mov_b64_e32 v[92:93], 0
	v_mov_b64_e32 v[94:95], 0
	v_mov_b64_e32 v[96:97], 0
	v_mov_b64_e32 v[98:99], 0
	v_mov_b64_e32 v[100:101], 0
	v_mov_b64_e32 v[102:103], 0
	v_mov_b64_e32 v[104:105], 0
	v_mov_b64_e32 v[106:107], 0
	v_mov_b64_e32 v[108:109], 0
	v_mov_b64_e32 v[110:111], 0
	v_mov_b64_e32 v[112:113], 0
	v_mov_b64_e32 v[114:115], 0
	v_mov_b64_e32 v[116:117], 0
	v_mov_b64_e32 v[118:119], 0
	v_mov_b64_e32 v[120:121], 0
	v_mov_b64_e32 v[122:123], 0
	v_mov_b64_e32 v[124:125], 0
	v_mov_b64_e32 v[126:127], 0
	v_mov_b64_e32 v[128:129], 0

.LBB0_115:
	s_ashr_i32 s23, s22, 31
	s_lshl_b64 s[24:25], s[22:23], 20
	s_add_u32 s24, s38, s24
	s_addc_u32 s25, s39, s25
	s_and_b64 s[26:27], s[4:5], exec
	s_cselect_b32 s23, s25, s7
	s_cselect_b32 s28, s24, s6
	s_ashr_i32 s21, s20, 31
	s_lshl_b64 s[26:27], s[20:21], 20
	s_add_u32 s26, s40, s26
	s_addc_u32 s27, s41, s27
	s_and_b64 s[34:35], s[4:5], exec
	s_cselect_b32 s21, s27, s31
	s_cselect_b32 s29, s26, s30
	s_add_u32 s6, s6, 0x80080
	s_addc_u32 s7, s7, 0
	s_add_u32 s49, s30, 0x100
	s_addc_u32 s50, s31, 0
	s_mov_b32 s51, -2
	v_mov_b64_e32 v[2:3], 0
	v_mov_b64_e32 v[4:5], 0
	v_mov_b64_e32 v[6:7], 0
	v_mov_b64_e32 v[8:9], 0
	v_mov_b64_e32 v[10:11], 0
	v_mov_b64_e32 v[12:13], 0
	v_mov_b64_e32 v[14:15], 0
	v_mov_b64_e32 v[16:17], 0
	v_mov_b64_e32 v[18:19], 0
	v_mov_b64_e32 v[20:21], 0
	v_mov_b64_e32 v[22:23], 0
	v_mov_b64_e32 v[24:25], 0
	v_mov_b64_e32 v[26:27], 0
	v_mov_b64_e32 v[28:29], 0
	v_mov_b64_e32 v[30:31], 0
	v_mov_b64_e32 v[32:33], 0
	v_mov_b64_e32 v[34:35], 0
	v_mov_b64_e32 v[36:37], 0
	v_mov_b64_e32 v[38:39], 0
	v_mov_b64_e32 v[40:41], 0
	v_mov_b64_e32 v[42:43], 0
	v_mov_b64_e32 v[44:45], 0
	v_mov_b64_e32 v[46:47], 0
	v_mov_b64_e32 v[48:49], 0
	v_mov_b64_e32 v[50:51], 0
	v_mov_b64_e32 v[52:53], 0
	v_mov_b64_e32 v[54:55], 0
	v_mov_b64_e32 v[56:57], 0
	v_mov_b64_e32 v[58:59], 0
	v_mov_b64_e32 v[60:61], 0
	v_mov_b64_e32 v[62:63], 0
	v_mov_b64_e32 v[64:65], 0
	v_mov_b64_e32 v[94:95], 0
	v_mov_b64_e32 v[96:97], 0
	v_mov_b64_e32 v[102:103], 0
	v_mov_b64_e32 v[104:105], 0
	v_mov_b64_e32 v[106:107], 0
	v_mov_b64_e32 v[108:109], 0
	v_mov_b64_e32 v[110:111], 0
	v_mov_b64_e32 v[112:113], 0
	v_mov_b64_e32 v[114:115], 0
	v_mov_b64_e32 v[116:117], 0
	v_mov_b64_e32 v[118:119], 0
	v_mov_b64_e32 v[120:121], 0
	v_mov_b64_e32 v[122:123], 0
	v_mov_b64_e32 v[124:125], 0
	v_mov_b64_e32 v[126:127], 0
	v_mov_b64_e32 v[128:129], 0
	v_mov_b64_e32 v[130:131], 0
	v_mov_b64_e32 v[132:133], 0
	v_mov_b64_e32 v[134:135], 0
	v_mov_b64_e32 v[136:137], 0
	v_mov_b64_e32 v[138:139], 0
	v_mov_b64_e32 v[140:141], 0
	v_mov_b64_e32 v[142:143], 0
	v_mov_b64_e32 v[144:145], 0
	v_mov_b64_e32 v[146:147], 0
	v_mov_b64_e32 v[148:149], 0
	v_mov_b64_e32 v[150:151], 0
	v_mov_b64_e32 v[152:153], 0
	v_mov_b64_e32 v[154:155], 0
	v_mov_b64_e32 v[156:157], 0
	v_mov_b64_e32 v[158:159], 0
	v_mov_b64_e32 v[160:161], 0

.LBB0_225:
	s_ashr_i32 s23, s22, 31
	s_lshl_b64 s[24:25], s[22:23], 20
	s_add_u32 s24, s38, s24
	s_addc_u32 s25, s39, s25
	s_and_b64 s[26:27], s[6:7], exec
	s_cselect_b32 s23, s25, s9
	s_cselect_b32 s28, s24, s8
	s_ashr_i32 s21, s20, 31
	s_lshl_b64 s[26:27], s[20:21], 20
	s_add_u32 s26, s36, s26
	s_addc_u32 s27, s37, s27
	s_and_b64 s[34:35], s[6:7], exec
	s_cselect_b32 s21, s27, s31
	s_cselect_b32 s29, s26, s30
	s_add_u32 s8, s8, 0x80080
	s_addc_u32 s9, s9, 0
	s_add_u32 s51, s30, 0x100
	s_addc_u32 s52, s31, 0
	s_mov_b32 s53, -2
	v_mov_b64_e32 v[2:3], 0
	v_mov_b64_e32 v[4:5], 0
	v_mov_b64_e32 v[6:7], 0
	v_mov_b64_e32 v[8:9], 0
	v_mov_b64_e32 v[10:11], 0
	v_mov_b64_e32 v[12:13], 0
	v_mov_b64_e32 v[14:15], 0
	v_mov_b64_e32 v[16:17], 0
	v_mov_b64_e32 v[18:19], 0
	v_mov_b64_e32 v[20:21], 0
	v_mov_b64_e32 v[22:23], 0
	v_mov_b64_e32 v[24:25], 0
	v_mov_b64_e32 v[26:27], 0
	v_mov_b64_e32 v[28:29], 0
	v_mov_b64_e32 v[30:31], 0
	v_mov_b64_e32 v[32:33], 0
	v_mov_b64_e32 v[34:35], 0
	v_mov_b64_e32 v[36:37], 0
	v_mov_b64_e32 v[38:39], 0
	v_mov_b64_e32 v[40:41], 0
	v_mov_b64_e32 v[42:43], 0
	v_mov_b64_e32 v[44:45], 0
	v_mov_b64_e32 v[46:47], 0
	v_mov_b64_e32 v[48:49], 0
	v_mov_b64_e32 v[50:51], 0
	v_mov_b64_e32 v[52:53], 0
	v_mov_b64_e32 v[54:55], 0
	v_mov_b64_e32 v[56:57], 0
	v_mov_b64_e32 v[58:59], 0
	v_mov_b64_e32 v[60:61], 0
	v_mov_b64_e32 v[62:63], 0
	v_mov_b64_e32 v[64:65], 0
	v_mov_b64_e32 v[66:67], 0
	v_mov_b64_e32 v[68:69], 0
	v_mov_b64_e32 v[70:71], 0
	v_mov_b64_e32 v[72:73], 0
	v_mov_b64_e32 v[74:75], 0
	v_mov_b64_e32 v[76:77], 0
	v_mov_b64_e32 v[78:79], 0
	v_mov_b64_e32 v[80:81], 0
	v_mov_b64_e32 v[82:83], 0
	v_mov_b64_e32 v[84:85], 0
	v_mov_b64_e32 v[86:87], 0
	v_mov_b64_e32 v[88:89], 0
	v_mov_b64_e32 v[90:91], 0
	v_mov_b64_e32 v[92:93], 0
	v_mov_b64_e32 v[94:95], 0
	v_mov_b64_e32 v[96:97], 0
	v_mov_b64_e32 v[98:99], 0
	v_mov_b64_e32 v[100:101], 0
	v_mov_b64_e32 v[102:103], 0
	v_mov_b64_e32 v[104:105], 0
	v_mov_b64_e32 v[106:107], 0
	v_mov_b64_e32 v[108:109], 0
	v_mov_b64_e32 v[110:111], 0
	v_mov_b64_e32 v[112:113], 0
	v_mov_b64_e32 v[114:115], 0
	v_mov_b64_e32 v[116:117], 0
	v_mov_b64_e32 v[118:119], 0
	v_mov_b64_e32 v[120:121], 0
	v_mov_b64_e32 v[122:123], 0
	v_mov_b64_e32 v[124:125], 0
	v_mov_b64_e32 v[126:127], 0
	v_mov_b64_e32 v[128:129], 0

.LBB0_955:
	s_ashr_i32 s37, s36, 31
	s_lshl_b64 s[2:3], s[36:37], 20
	s_add_u32 s38, s45, s2
	s_addc_u32 s39, s48, s3
	s_and_b64 s[2:3], s[8:9], exec
	s_cselect_b32 s2, s39, s35
	s_cselect_b32 s3, s38, s34
	s_ashr_i32 s31, s30, 31
	s_lshl_b64 s[10:11], s[30:31], 20
	s_add_u32 s40, s49, s10
	s_addc_u32 s41, s50, s11
	s_and_b64 s[10:11], s[8:9], exec
	s_cselect_b32 s31, s41, s43
	s_cselect_b32 s37, s40, s42
	s_add_u32 s60, s42, 0x100
	s_addc_u32 s61, s43, 0
	s_mov_b32 s62, -2
	v_mov_b64_e32 v[2:3], 0
	v_mov_b64_e32 v[4:5], 0
	v_mov_b64_e32 v[6:7], 0
	v_mov_b64_e32 v[8:9], 0
	v_mov_b64_e32 v[10:11], 0
	v_mov_b64_e32 v[12:13], 0
	v_mov_b64_e32 v[14:15], 0
	v_mov_b64_e32 v[16:17], 0
	v_mov_b64_e32 v[18:19], 0
	v_mov_b64_e32 v[20:21], 0
	v_mov_b64_e32 v[22:23], 0
	v_mov_b64_e32 v[24:25], 0
	v_mov_b64_e32 v[26:27], 0
	v_mov_b64_e32 v[28:29], 0
	v_mov_b64_e32 v[30:31], 0
	v_mov_b64_e32 v[32:33], 0
	v_mov_b64_e32 v[34:35], 0
	v_mov_b64_e32 v[36:37], 0
	v_mov_b64_e32 v[38:39], 0
	v_mov_b64_e32 v[40:41], 0
	v_mov_b64_e32 v[42:43], 0
	v_mov_b64_e32 v[44:45], 0
	v_mov_b64_e32 v[46:47], 0
	v_mov_b64_e32 v[48:49], 0
	v_mov_b64_e32 v[50:51], 0
	v_mov_b64_e32 v[52:53], 0
	v_mov_b64_e32 v[54:55], 0
	v_mov_b64_e32 v[56:57], 0
	v_mov_b64_e32 v[58:59], 0
	v_mov_b64_e32 v[60:61], 0
	v_mov_b64_e32 v[62:63], 0
	v_mov_b64_e32 v[64:65], 0
	v_mov_b64_e32 v[98:99], 0
	v_mov_b64_e32 v[100:101], 0
	v_mov_b64_e32 v[102:103], 0
	v_mov_b64_e32 v[104:105], 0
	v_mov_b64_e32 v[106:107], 0
	v_mov_b64_e32 v[108:109], 0
	v_mov_b64_e32 v[110:111], 0
	v_mov_b64_e32 v[112:113], 0
	v_mov_b64_e32 v[114:115], 0
	v_mov_b64_e32 v[116:117], 0
	v_mov_b64_e32 v[118:119], 0
	v_mov_b64_e32 v[120:121], 0
	v_mov_b64_e32 v[122:123], 0
	v_mov_b64_e32 v[124:125], 0
	v_mov_b64_e32 v[126:127], 0
	v_mov_b64_e32 v[128:129], 0
	v_mov_b64_e32 v[130:131], 0
	v_mov_b64_e32 v[132:133], 0
	v_mov_b64_e32 v[134:135], 0
	v_mov_b64_e32 v[136:137], 0
	v_mov_b64_e32 v[138:139], 0
	v_mov_b64_e32 v[140:141], 0
	v_mov_b64_e32 v[142:143], 0
	v_mov_b64_e32 v[144:145], 0
	v_mov_b64_e32 v[146:147], 0
	v_mov_b64_e32 v[148:149], 0
	v_mov_b64_e32 v[150:151], 0
	v_mov_b64_e32 v[152:153], 0
	v_mov_b64_e32 v[154:155], 0
	v_mov_b64_e32 v[156:157], 0
	v_mov_b64_e32 v[158:159], 0
	v_mov_b64_e32 v[160:161], 0

.LBB0_1090:
	s_ashr_i32 s21, s20, 31
	s_lshl_b64 s[2:3], s[20:21], 20
	s_add_u32 s22, s36, s2
	s_addc_u32 s23, s37, s3
	s_and_b64 s[2:3], s[6:7], exec
	s_cselect_b32 s2, s23, s27
	s_cselect_b32 s3, s22, s26
	s_ashr_i32 s19, s18, 31
	s_lshl_b64 s[24:25], s[18:19], 20
	s_add_u32 s24, s38, s24
	s_addc_u32 s25, s39, s25
	s_and_b64 s[34:35], s[6:7], exec
	s_cselect_b32 s19, s25, s31
	s_cselect_b32 s21, s24, s30
	s_add_u32 s26, s26, 0x80080
	s_addc_u32 s27, s27, 0
	s_add_u32 s48, s30, 0x100
	s_addc_u32 s49, s31, 0
	s_mov_b32 s50, -2
	v_mov_b64_e32 v[2:3], 0
	v_mov_b64_e32 v[4:5], 0
	v_mov_b64_e32 v[6:7], 0
	v_mov_b64_e32 v[8:9], 0
	v_mov_b64_e32 v[10:11], 0
	v_mov_b64_e32 v[12:13], 0
	v_mov_b64_e32 v[14:15], 0
	v_mov_b64_e32 v[16:17], 0
	v_mov_b64_e32 v[18:19], 0
	v_mov_b64_e32 v[20:21], 0
	v_mov_b64_e32 v[22:23], 0
	v_mov_b64_e32 v[24:25], 0
	v_mov_b64_e32 v[26:27], 0
	v_mov_b64_e32 v[28:29], 0
	v_mov_b64_e32 v[30:31], 0
	v_mov_b64_e32 v[32:33], 0
	v_mov_b64_e32 v[34:35], 0
	v_mov_b64_e32 v[36:37], 0
	v_mov_b64_e32 v[38:39], 0
	v_mov_b64_e32 v[40:41], 0
	v_mov_b64_e32 v[42:43], 0
	v_mov_b64_e32 v[44:45], 0
	v_mov_b64_e32 v[46:47], 0
	v_mov_b64_e32 v[48:49], 0
	v_mov_b64_e32 v[50:51], 0
	v_mov_b64_e32 v[52:53], 0
	v_mov_b64_e32 v[54:55], 0
	v_mov_b64_e32 v[56:57], 0
	v_mov_b64_e32 v[58:59], 0
	v_mov_b64_e32 v[60:61], 0
	v_mov_b64_e32 v[62:63], 0
	v_mov_b64_e32 v[64:65], 0
	v_mov_b64_e32 v[66:67], 0
	v_mov_b64_e32 v[68:69], 0
	v_mov_b64_e32 v[70:71], 0
	v_mov_b64_e32 v[72:73], 0
	v_mov_b64_e32 v[74:75], 0
	v_mov_b64_e32 v[76:77], 0
	v_mov_b64_e32 v[78:79], 0
	v_mov_b64_e32 v[80:81], 0
	v_mov_b64_e32 v[82:83], 0
	v_mov_b64_e32 v[84:85], 0
	v_mov_b64_e32 v[86:87], 0
	v_mov_b64_e32 v[88:89], 0
	v_mov_b64_e32 v[90:91], 0
	v_mov_b64_e32 v[92:93], 0
	v_mov_b64_e32 v[94:95], 0
	v_mov_b64_e32 v[96:97], 0
	v_mov_b64_e32 v[98:99], 0
	v_mov_b64_e32 v[100:101], 0
	v_mov_b64_e32 v[102:103], 0
	v_mov_b64_e32 v[104:105], 0
	v_mov_b64_e32 v[106:107], 0
	v_mov_b64_e32 v[108:109], 0
	v_mov_b64_e32 v[110:111], 0
	v_mov_b64_e32 v[112:113], 0
	v_mov_b64_e32 v[114:115], 0
	v_mov_b64_e32 v[116:117], 0
	v_mov_b64_e32 v[118:119], 0
	v_mov_b64_e32 v[120:121], 0
	v_mov_b64_e32 v[122:123], 0
	v_mov_b64_e32 v[124:125], 0
	v_mov_b64_e32 v[126:127], 0
	v_mov_b64_e32 v[128:129], 0

.LBB0_1179:
	s_ashr_i32 s25, s24, 31
	s_lshl_b64 s[2:3], s[24:25], 22
	s_add_u32 s26, s42, s2
	s_addc_u32 s27, s43, s3
	s_and_b64 s[2:3], s[6:7], exec
	s_cselect_b32 s2, s27, s35
	s_cselect_b32 s3, s26, s34
	s_ashr_i32 s23, s22, 31
	s_lshl_b64 s[30:31], s[22:23], 22
	s_add_u32 s30, s44, s30
	s_addc_u32 s31, s45, s31
	s_and_b64 s[38:39], s[6:7], exec
	s_cselect_b32 s23, s31, s37
	s_cselect_b32 s25, s30, s36
	s_add_u32 s54, s36, 0x100
	s_addc_u32 s55, s37, 0
	s_mov_b32 s56, -2
	v_mov_b64_e32 v[2:3], 0
	v_mov_b64_e32 v[4:5], 0
	v_mov_b64_e32 v[6:7], 0
	v_mov_b64_e32 v[8:9], 0
	v_mov_b64_e32 v[10:11], 0
	v_mov_b64_e32 v[12:13], 0
	v_mov_b64_e32 v[14:15], 0
	v_mov_b64_e32 v[16:17], 0
	v_mov_b64_e32 v[18:19], 0
	v_mov_b64_e32 v[20:21], 0
	v_mov_b64_e32 v[22:23], 0
	v_mov_b64_e32 v[24:25], 0
	v_mov_b64_e32 v[26:27], 0
	v_mov_b64_e32 v[28:29], 0
	v_mov_b64_e32 v[30:31], 0
	v_mov_b64_e32 v[32:33], 0
	v_mov_b64_e32 v[34:35], 0
	v_mov_b64_e32 v[36:37], 0
	v_mov_b64_e32 v[38:39], 0
	v_mov_b64_e32 v[40:41], 0
	v_mov_b64_e32 v[42:43], 0
	v_mov_b64_e32 v[44:45], 0
	v_mov_b64_e32 v[46:47], 0
	v_mov_b64_e32 v[48:49], 0
	v_mov_b64_e32 v[50:51], 0
	v_mov_b64_e32 v[52:53], 0
	v_mov_b64_e32 v[54:55], 0
	v_mov_b64_e32 v[56:57], 0
	v_mov_b64_e32 v[58:59], 0
	v_mov_b64_e32 v[60:61], 0
	v_mov_b64_e32 v[62:63], 0
	v_mov_b64_e32 v[64:65], 0
	v_mov_b64_e32 v[90:91], 0
	v_mov_b64_e32 v[92:93], 0
	v_mov_b64_e32 v[102:103], 0
	v_mov_b64_e32 v[104:105], 0
	v_mov_b64_e32 v[106:107], 0
	v_mov_b64_e32 v[108:109], 0
	v_mov_b64_e32 v[110:111], 0
	v_mov_b64_e32 v[112:113], 0
	v_mov_b64_e32 v[114:115], 0
	v_mov_b64_e32 v[116:117], 0
	v_mov_b64_e32 v[118:119], 0
	v_mov_b64_e32 v[120:121], 0
	v_mov_b64_e32 v[122:123], 0
	v_mov_b64_e32 v[124:125], 0
	v_mov_b64_e32 v[126:127], 0
	v_mov_b64_e32 v[128:129], 0
	v_mov_b64_e32 v[130:131], 0
	v_mov_b64_e32 v[132:133], 0
	v_mov_b64_e32 v[134:135], 0
	v_mov_b64_e32 v[136:137], 0
	v_mov_b64_e32 v[138:139], 0
	v_mov_b64_e32 v[140:141], 0
	v_mov_b64_e32 v[142:143], 0
	v_mov_b64_e32 v[144:145], 0
	v_mov_b64_e32 v[146:147], 0
	v_mov_b64_e32 v[148:149], 0
	v_mov_b64_e32 v[150:151], 0
	v_mov_b64_e32 v[152:153], 0
	v_mov_b64_e32 v[154:155], 0
	v_mov_b64_e32 v[156:157], 0
	v_mov_b64_e32 v[158:159], 0
	v_mov_b64_e32 v[160:161], 0
